# v1 attention loop + EpiResid epilogue rewritten: pipelined x loads (6 in flight), saddr+voffset addressing
# speedup vs baseline: 1.0035x; 1.0035x over previous
.LBB0_293:
	s_ashr_i32 s3, s65, 31
	s_sub_i32 s4, s65, 64
	s_lshr_b32 s24, s65, 4
	s_cmp_gt_i32 s65, 63
	s_cselect_b32 s5, 0, s3
	s_cselect_b32 s4, s4, s65
	s_mulk_i32 s24, 0x4800
	s_waitcnt lgkmcnt(0)
	s_cselect_b32 s3, s15, s91
	s_cselect_b32 s28, s14, s90
	s_cselect_b32 s35, s14, s72
	s_cselect_b32 s42, s15, s73
	s_cselect_b32 s34, 0x12000, s24
	s_lshl_b64 s[4:5], s[4:5], 20
	s_add_u32 s28, s28, s4
	s_addc_u32 s29, s3, s5
	s_add_u32 s4, s35, s4
	s_addc_u32 s5, s42, s5
	s_ashr_i32 s35, s34, 31
	s_lshl_b32 s3, s85, 8
	s_or_b32 s3, s3, s1
	s_lshl_b64 s[34:35], s[34:35], 2
	s_add_u32 s34, s58, s34
	v_lshl_add_u32 v154, v67, 2, s3
	s_addc_u32 s35, s92, s35
	v_ashrrev_i32_e32 v155, 31, v154
	v_lshl_add_u64 v[156:157], v[154:155], 2, s[34:35]
	global_load_dwordx4 v[132:135], v[156:157], off
	global_load_dwordx4 v[136:139], v[156:157], off offset:64
	global_load_dwordx4 v[140:143], v[156:157], off offset:512
	global_load_dwordx4 v[168:171], v[156:157], off offset:576
	v_add_u32_e32 v163, s0, v164
	v_lshlrev_b32_e32 v163, 12, v163
	v_lshl_add_u32 v162, v154, 2, v163
	s_andn2_b64 vcc, exec, s[30:31]
	s_cbranch_vccz .Lepi_r_split
	global_load_dwordx4 v[150:153], v162, s[28:29]
	global_load_dwordx4 v[154:157], v162, s[28:29] offset:64
	global_load_dwordx4 v[158:161], v162, s[28:29] offset:512
	global_load_dwordx4 v[244:247], v162, s[28:29] offset:576
	s_add_u32 s28, s28, 0x10000
	s_addc_u32 s29, s29, 0
	global_load_dwordx4 v[248:251], v162, s[28:29]
	global_load_dwordx4 v[252:255], v162, s[28:29] offset:64
	s_waitcnt vmcnt(6)
	v_mul_f32_e32 v132, s88, v132
	v_mul_f32_e32 v133, s88, v133
	v_mul_f32_e32 v134, s88, v134
	v_mul_f32_e32 v135, s88, v135
	v_mul_f32_e32 v136, s88, v136
	v_mul_f32_e32 v137, s88, v137
	v_mul_f32_e32 v138, s88, v138
	v_mul_f32_e32 v139, s88, v139
	v_mul_f32_e32 v140, s88, v140
	v_mul_f32_e32 v141, s88, v141
	v_mul_f32_e32 v142, s88, v142
	v_mul_f32_e32 v143, s88, v143
	v_mul_f32_e32 v168, s88, v168
	v_mul_f32_e32 v169, s88, v169
	v_mul_f32_e32 v170, s88, v170
	v_mul_f32_e32 v171, s88, v171
	s_waitcnt vmcnt(4)
	v_pk_fma_f32 v[128:129], v[128:129], v[132:133], v[150:151]
	v_pk_fma_f32 v[130:131], v[130:131], v[134:135], v[152:153]
	v_pk_fma_f32 v[124:125], v[124:125], v[136:137], v[154:155]
	v_pk_fma_f32 v[126:127], v[126:127], v[138:139], v[156:157]
	global_store_dwordx4 v162, v[128:131], s[4:5]
	global_store_dwordx4 v162, v[124:127], s[4:5] offset:64
	global_load_dwordx4 v[150:153], v162, s[28:29] offset:512
	global_load_dwordx4 v[154:157], v162, s[28:29] offset:576
	s_waitcnt vmcnt(6)
	v_pk_fma_f32 v[120:121], v[120:121], v[140:141], v[158:159]
	v_pk_fma_f32 v[122:123], v[122:123], v[142:143], v[160:161]
	v_pk_fma_f32 v[116:117], v[116:117], v[168:169], v[244:245]
	v_pk_fma_f32 v[118:119], v[118:119], v[170:171], v[246:247]
	global_store_dwordx4 v162, v[120:123], s[4:5] offset:512
	global_store_dwordx4 v162, v[116:119], s[4:5] offset:576
	s_add_u32 s28, s28, 0x10000
	s_addc_u32 s29, s29, 0
	global_load_dwordx4 v[158:161], v162, s[28:29]
	global_load_dwordx4 v[244:247], v162, s[28:29] offset:64
	s_waitcnt vmcnt(8)
	v_pk_fma_f32 v[112:113], v[112:113], v[132:133], v[248:249]
	v_pk_fma_f32 v[114:115], v[114:115], v[134:135], v[250:251]
	v_pk_fma_f32 v[108:109], v[108:109], v[136:137], v[252:253]
	v_pk_fma_f32 v[110:111], v[110:111], v[138:139], v[254:255]
	s_add_u32 s4, s4, 0x10000
	s_addc_u32 s5, s5, 0
	global_store_dwordx4 v162, v[112:115], s[4:5]
	global_store_dwordx4 v162, v[108:111], s[4:5] offset:64
	global_load_dwordx4 v[248:251], v162, s[28:29] offset:512
	global_load_dwordx4 v[252:255], v162, s[28:29] offset:576
	s_waitcnt vmcnt(8)
	v_pk_fma_f32 v[104:105], v[104:105], v[140:141], v[150:151]
	v_pk_fma_f32 v[106:107], v[106:107], v[142:143], v[152:153]
	v_pk_fma_f32 v[100:101], v[100:101], v[168:169], v[154:155]
	v_pk_fma_f32 v[102:103], v[102:103], v[170:171], v[156:157]
	global_store_dwordx4 v162, v[104:107], s[4:5] offset:512
	global_store_dwordx4 v162, v[100:103], s[4:5] offset:576
	s_add_u32 s28, s28, 0x10000
	s_addc_u32 s29, s29, 0
	global_load_dwordx4 v[150:153], v162, s[28:29]
	global_load_dwordx4 v[154:157], v162, s[28:29] offset:64
	s_waitcnt vmcnt(8)
	v_pk_fma_f32 v[96:97], v[96:97], v[132:133], v[158:159]
	v_pk_fma_f32 v[98:99], v[98:99], v[134:135], v[160:161]
	v_pk_fma_f32 v[92:93], v[92:93], v[136:137], v[244:245]
	v_pk_fma_f32 v[94:95], v[94:95], v[138:139], v[246:247]
	s_add_u32 s4, s4, 0x10000
	s_addc_u32 s5, s5, 0
	global_store_dwordx4 v162, v[96:99], s[4:5]
	global_store_dwordx4 v162, v[92:95], s[4:5] offset:64
	global_load_dwordx4 v[158:161], v162, s[28:29] offset:512
	global_load_dwordx4 v[244:247], v162, s[28:29] offset:576
	s_waitcnt vmcnt(8)
	v_pk_fma_f32 v[88:89], v[88:89], v[140:141], v[248:249]
	v_pk_fma_f32 v[90:91], v[90:91], v[142:143], v[250:251]
	v_pk_fma_f32 v[84:85], v[84:85], v[168:169], v[252:253]
	v_pk_fma_f32 v[86:87], v[86:87], v[170:171], v[254:255]
	global_store_dwordx4 v162, v[88:91], s[4:5] offset:512
	global_store_dwordx4 v162, v[84:87], s[4:5] offset:576
	s_add_u32 s28, s28, 0x50000
	s_addc_u32 s29, s29, 0
	global_load_dwordx4 v[248:251], v162, s[28:29]
	global_load_dwordx4 v[252:255], v162, s[28:29] offset:64
	s_waitcnt vmcnt(8)
	v_pk_fma_f32 v[80:81], v[80:81], v[132:133], v[150:151]
	v_pk_fma_f32 v[82:83], v[82:83], v[134:135], v[152:153]
	v_pk_fma_f32 v[76:77], v[76:77], v[136:137], v[154:155]
	v_pk_fma_f32 v[78:79], v[78:79], v[138:139], v[156:157]
	s_add_u32 s4, s4, 0x10000
	s_addc_u32 s5, s5, 0
	global_store_dwordx4 v162, v[80:83], s[4:5]
	global_store_dwordx4 v162, v[76:79], s[4:5] offset:64
	global_load_dwordx4 v[150:153], v162, s[28:29] offset:512
	global_load_dwordx4 v[154:157], v162, s[28:29] offset:576
	s_waitcnt vmcnt(8)
	v_pk_fma_f32 v[72:73], v[72:73], v[140:141], v[158:159]
	v_pk_fma_f32 v[74:75], v[74:75], v[142:143], v[160:161]
	v_pk_fma_f32 v[68:69], v[68:69], v[168:169], v[244:245]
	v_pk_fma_f32 v[70:71], v[70:71], v[170:171], v[246:247]
	global_store_dwordx4 v162, v[72:75], s[4:5] offset:512
	global_store_dwordx4 v162, v[68:71], s[4:5] offset:576
	s_add_u32 s28, s28, 0x10000
	s_addc_u32 s29, s29, 0
	global_load_dwordx4 v[158:161], v162, s[28:29]
	global_load_dwordx4 v[244:247], v162, s[28:29] offset:64
	s_waitcnt vmcnt(8)
	v_pk_fma_f32 v[62:63], v[62:63], v[132:133], v[248:249]
	v_pk_fma_f32 v[64:65], v[64:65], v[134:135], v[250:251]
	v_pk_fma_f32 v[58:59], v[58:59], v[136:137], v[252:253]
	v_pk_fma_f32 v[60:61], v[60:61], v[138:139], v[254:255]
	s_add_u32 s4, s4, 0x50000
	s_addc_u32 s5, s5, 0
	global_store_dwordx4 v162, v[62:65], s[4:5]
	global_store_dwordx4 v162, v[58:61], s[4:5] offset:64
	global_load_dwordx4 v[248:251], v162, s[28:29] offset:512
	global_load_dwordx4 v[252:255], v162, s[28:29] offset:576
	s_waitcnt vmcnt(8)
	v_pk_fma_f32 v[54:55], v[54:55], v[140:141], v[150:151]
	v_pk_fma_f32 v[56:57], v[56:57], v[142:143], v[152:153]
	v_pk_fma_f32 v[50:51], v[50:51], v[168:169], v[154:155]
	v_pk_fma_f32 v[52:53], v[52:53], v[170:171], v[156:157]
	global_store_dwordx4 v162, v[54:57], s[4:5] offset:512
	global_store_dwordx4 v162, v[50:53], s[4:5] offset:576
	s_add_u32 s28, s28, 0x10000
	s_addc_u32 s29, s29, 0
	global_load_dwordx4 v[150:153], v162, s[28:29]
	global_load_dwordx4 v[154:157], v162, s[28:29] offset:64
	s_waitcnt vmcnt(8)
	v_pk_fma_f32 v[46:47], v[46:47], v[132:133], v[158:159]
	v_pk_fma_f32 v[48:49], v[48:49], v[134:135], v[160:161]
	v_pk_fma_f32 v[42:43], v[42:43], v[136:137], v[244:245]
	v_pk_fma_f32 v[44:45], v[44:45], v[138:139], v[246:247]
	s_add_u32 s4, s4, 0x10000
	s_addc_u32 s5, s5, 0
	global_store_dwordx4 v162, v[46:49], s[4:5]
	global_store_dwordx4 v162, v[42:45], s[4:5] offset:64
	global_load_dwordx4 v[158:161], v162, s[28:29] offset:512
	global_load_dwordx4 v[244:247], v162, s[28:29] offset:576
	s_waitcnt vmcnt(8)
	v_pk_fma_f32 v[38:39], v[38:39], v[140:141], v[248:249]
	v_pk_fma_f32 v[40:41], v[40:41], v[142:143], v[250:251]
	v_pk_fma_f32 v[34:35], v[34:35], v[168:169], v[252:253]
	v_pk_fma_f32 v[36:37], v[36:37], v[170:171], v[254:255]
	global_store_dwordx4 v162, v[38:41], s[4:5] offset:512
	global_store_dwordx4 v162, v[34:37], s[4:5] offset:576
	s_add_u32 s28, s28, 0x10000
	s_addc_u32 s29, s29, 0
	global_load_dwordx4 v[248:251], v162, s[28:29]
	global_load_dwordx4 v[252:255], v162, s[28:29] offset:64
	s_waitcnt vmcnt(8)
	v_pk_fma_f32 v[30:31], v[30:31], v[132:133], v[150:151]
	v_pk_fma_f32 v[32:33], v[32:33], v[134:135], v[152:153]
	v_pk_fma_f32 v[26:27], v[26:27], v[136:137], v[154:155]
	v_pk_fma_f32 v[28:29], v[28:29], v[138:139], v[156:157]
	s_add_u32 s4, s4, 0x10000
	s_addc_u32 s5, s5, 0
	global_store_dwordx4 v162, v[30:33], s[4:5]
	global_store_dwordx4 v162, v[26:29], s[4:5] offset:64
	global_load_dwordx4 v[150:153], v162, s[28:29] offset:512
	global_load_dwordx4 v[154:157], v162, s[28:29] offset:576
	s_waitcnt vmcnt(8)
	v_pk_fma_f32 v[22:23], v[22:23], v[140:141], v[158:159]
	v_pk_fma_f32 v[24:25], v[24:25], v[142:143], v[160:161]
	v_pk_fma_f32 v[18:19], v[18:19], v[168:169], v[244:245]
	v_pk_fma_f32 v[20:21], v[20:21], v[170:171], v[246:247]
	global_store_dwordx4 v162, v[22:25], s[4:5] offset:512
	global_store_dwordx4 v162, v[18:21], s[4:5] offset:576
	s_waitcnt vmcnt(6)
	v_pk_fma_f32 v[14:15], v[14:15], v[132:133], v[248:249]
	v_pk_fma_f32 v[16:17], v[16:17], v[134:135], v[250:251]
	v_pk_fma_f32 v[10:11], v[10:11], v[136:137], v[252:253]
	v_pk_fma_f32 v[12:13], v[12:13], v[138:139], v[254:255]
	s_add_u32 s4, s4, 0x10000
	s_addc_u32 s5, s5, 0
	global_store_dwordx4 v162, v[14:17], s[4:5]
	global_store_dwordx4 v162, v[10:13], s[4:5] offset:64
	s_waitcnt vmcnt(4)
	v_pk_fma_f32 v[6:7], v[6:7], v[140:141], v[150:151]
	v_pk_fma_f32 v[8:9], v[8:9], v[142:143], v[152:153]
	v_pk_fma_f32 v[2:3], v[2:3], v[168:169], v[154:155]
	v_pk_fma_f32 v[4:5], v[4:5], v[170:171], v[156:157]
	global_store_dwordx4 v162, v[6:9], s[4:5] offset:512
	global_store_dwordx4 v162, v[2:5], s[4:5] offset:576
	s_branch .Lepi_r_done
.Lepi_r_split:
	s_lshl_b32 s3, s65, 8
	s_ashr_i32 s85, s84, 31
	s_add_i32 s30, s3, 0xffffc000
	s_ashr_i32 s31, s30, 31
	s_lshl_b64 s[34:35], s[84:85], 22
	s_add_u32 s3, s93, s34
	s_addc_u32 s24, s53, s35
	s_lshl_b64 s[30:31], s[30:31], 12
	s_add_u32 s30, s3, s30
	s_addc_u32 s31, s24, s31
	s_waitcnt vmcnt(0)
	v_mul_f32_e32 v132, s88, v132
	v_mul_f32_e32 v133, s88, v133
	v_mul_f32_e32 v134, s88, v134
	v_mul_f32_e32 v135, s88, v135
	v_mul_f32_e32 v136, s88, v136
	v_mul_f32_e32 v137, s88, v137
	v_mul_f32_e32 v138, s88, v138
	v_mul_f32_e32 v139, s88, v139
	v_mul_f32_e32 v140, s88, v140
	v_mul_f32_e32 v141, s88, v141
	v_mul_f32_e32 v142, s88, v142
	v_mul_f32_e32 v143, s88, v143
	v_mul_f32_e32 v168, s88, v168
	v_mul_f32_e32 v169, s88, v169
	v_mul_f32_e32 v170, s88, v170
	v_mul_f32_e32 v171, s88, v171
	v_pk_mul_f32 v[150:151], v[132:133], v[128:129]
	v_pk_mul_f32 v[152:153], v[134:135], v[130:131]
	global_store_dwordx4 v162, v[150:153], s[30:31]
	v_pk_mul_f32 v[154:155], v[136:137], v[124:125]
	v_pk_mul_f32 v[156:157], v[138:139], v[126:127]
	global_store_dwordx4 v162, v[154:157], s[30:31] offset:64
	v_pk_mul_f32 v[158:159], v[140:141], v[120:121]
	v_pk_mul_f32 v[160:161], v[142:143], v[122:123]
	global_store_dwordx4 v162, v[158:161], s[30:31] offset:512
	v_pk_mul_f32 v[244:245], v[168:169], v[116:117]
	v_pk_mul_f32 v[246:247], v[170:171], v[118:119]
	global_store_dwordx4 v162, v[244:247], s[30:31] offset:576
	s_add_u32 s30, s30, 0x10000
	s_addc_u32 s31, s31, 0
	v_pk_mul_f32 v[248:249], v[132:133], v[112:113]
	v_pk_mul_f32 v[250:251], v[134:135], v[114:115]
	global_store_dwordx4 v162, v[248:251], s[30:31]
	v_pk_mul_f32 v[252:253], v[136:137], v[108:109]
	v_pk_mul_f32 v[254:255], v[138:139], v[110:111]
	global_store_dwordx4 v162, v[252:255], s[30:31] offset:64
	v_pk_mul_f32 v[150:151], v[140:141], v[104:105]
	v_pk_mul_f32 v[152:153], v[142:143], v[106:107]
	global_store_dwordx4 v162, v[150:153], s[30:31] offset:512
	v_pk_mul_f32 v[154:155], v[168:169], v[100:101]
	v_pk_mul_f32 v[156:157], v[170:171], v[102:103]
	global_store_dwordx4 v162, v[154:157], s[30:31] offset:576
	s_add_u32 s30, s30, 0x10000
	s_addc_u32 s31, s31, 0
	v_pk_mul_f32 v[158:159], v[132:133], v[96:97]
	v_pk_mul_f32 v[160:161], v[134:135], v[98:99]
	global_store_dwordx4 v162, v[158:161], s[30:31]
	v_pk_mul_f32 v[244:245], v[136:137], v[92:93]
	v_pk_mul_f32 v[246:247], v[138:139], v[94:95]
	global_store_dwordx4 v162, v[244:247], s[30:31] offset:64
	v_pk_mul_f32 v[248:249], v[140:141], v[88:89]
	v_pk_mul_f32 v[250:251], v[142:143], v[90:91]
	global_store_dwordx4 v162, v[248:251], s[30:31] offset:512
	v_pk_mul_f32 v[252:253], v[168:169], v[84:85]
	v_pk_mul_f32 v[254:255], v[170:171], v[86:87]
	global_store_dwordx4 v162, v[252:255], s[30:31] offset:576
	s_add_u32 s30, s30, 0x10000
	s_addc_u32 s31, s31, 0
	v_pk_mul_f32 v[150:151], v[132:133], v[80:81]
	v_pk_mul_f32 v[152:153], v[134:135], v[82:83]
	global_store_dwordx4 v162, v[150:153], s[30:31]
	v_pk_mul_f32 v[154:155], v[136:137], v[76:77]
	v_pk_mul_f32 v[156:157], v[138:139], v[78:79]
	global_store_dwordx4 v162, v[154:157], s[30:31] offset:64
	v_pk_mul_f32 v[158:159], v[140:141], v[72:73]
	v_pk_mul_f32 v[160:161], v[142:143], v[74:75]
	global_store_dwordx4 v162, v[158:161], s[30:31] offset:512
	v_pk_mul_f32 v[244:245], v[168:169], v[68:69]
	v_pk_mul_f32 v[246:247], v[170:171], v[70:71]
	global_store_dwordx4 v162, v[244:247], s[30:31] offset:576
	s_add_u32 s30, s30, 0x50000
	s_addc_u32 s31, s31, 0
	v_pk_mul_f32 v[248:249], v[132:133], v[62:63]
	v_pk_mul_f32 v[250:251], v[134:135], v[64:65]
	global_store_dwordx4 v162, v[248:251], s[30:31]
	v_pk_mul_f32 v[252:253], v[136:137], v[58:59]
	v_pk_mul_f32 v[254:255], v[138:139], v[60:61]
	global_store_dwordx4 v162, v[252:255], s[30:31] offset:64
	v_pk_mul_f32 v[150:151], v[140:141], v[54:55]
	v_pk_mul_f32 v[152:153], v[142:143], v[56:57]
	global_store_dwordx4 v162, v[150:153], s[30:31] offset:512
	v_pk_mul_f32 v[154:155], v[168:169], v[50:51]
	v_pk_mul_f32 v[156:157], v[170:171], v[52:53]
	global_store_dwordx4 v162, v[154:157], s[30:31] offset:576
	s_add_u32 s30, s30, 0x10000
	s_addc_u32 s31, s31, 0
	v_pk_mul_f32 v[158:159], v[132:133], v[46:47]
	v_pk_mul_f32 v[160:161], v[134:135], v[48:49]
	global_store_dwordx4 v162, v[158:161], s[30:31]
	v_pk_mul_f32 v[244:245], v[136:137], v[42:43]
	v_pk_mul_f32 v[246:247], v[138:139], v[44:45]
	global_store_dwordx4 v162, v[244:247], s[30:31] offset:64
	v_pk_mul_f32 v[248:249], v[140:141], v[38:39]
	v_pk_mul_f32 v[250:251], v[142:143], v[40:41]
	global_store_dwordx4 v162, v[248:251], s[30:31] offset:512
	v_pk_mul_f32 v[252:253], v[168:169], v[34:35]
	v_pk_mul_f32 v[254:255], v[170:171], v[36:37]
	global_store_dwordx4 v162, v[252:255], s[30:31] offset:576
	s_add_u32 s30, s30, 0x10000
	s_addc_u32 s31, s31, 0
	v_pk_mul_f32 v[150:151], v[132:133], v[30:31]
	v_pk_mul_f32 v[152:153], v[134:135], v[32:33]
	global_store_dwordx4 v162, v[150:153], s[30:31]
	v_pk_mul_f32 v[154:155], v[136:137], v[26:27]
	v_pk_mul_f32 v[156:157], v[138:139], v[28:29]
	global_store_dwordx4 v162, v[154:157], s[30:31] offset:64
	v_pk_mul_f32 v[158:159], v[140:141], v[22:23]
	v_pk_mul_f32 v[160:161], v[142:143], v[24:25]
	global_store_dwordx4 v162, v[158:161], s[30:31] offset:512
	v_pk_mul_f32 v[244:245], v[168:169], v[18:19]
	v_pk_mul_f32 v[246:247], v[170:171], v[20:21]
	global_store_dwordx4 v162, v[244:247], s[30:31] offset:576
	s_add_u32 s30, s30, 0x10000
	s_addc_u32 s31, s31, 0
	v_pk_mul_f32 v[248:249], v[132:133], v[14:15]
	v_pk_mul_f32 v[250:251], v[134:135], v[16:17]
	global_store_dwordx4 v162, v[248:251], s[30:31]
	v_pk_mul_f32 v[252:253], v[136:137], v[10:11]
	v_pk_mul_f32 v[254:255], v[138:139], v[12:13]
	global_store_dwordx4 v162, v[252:255], s[30:31] offset:64
	v_pk_mul_f32 v[150:151], v[140:141], v[6:7]
	v_pk_mul_f32 v[152:153], v[142:143], v[8:9]
	global_store_dwordx4 v162, v[150:153], s[30:31] offset:512
	v_pk_mul_f32 v[154:155], v[168:169], v[2:3]
	v_pk_mul_f32 v[156:157], v[170:171], v[4:5]
	global_store_dwordx4 v162, v[154:157], s[30:31] offset:576
.Lepi_r_done:
	s_and_b64 vcc, exec, s[40:41]
	s_mov_b64 s[4:5], -1
	s_cbranch_vccnz .LBB0_270
	s_and_b64 s[4:5], s[38:39], exec
	s_cselect_b32 s84, 0, s25
	s_andn2_b64 vcc, exec, s[76:77]
	s_cbranch_vccnz .LBB0_269
	s_barrier
	s_branch .LBB0_269
